# local-phase unit distribution: one unit of each kind per workgroup, left-over heavy units replace prep units of WGs 0-23
# speedup vs baseline: 1.3777x; 1.0028x over previous
.LBB0_270:
	s_or_b64 exec, exec, s[0:1]
	v_readlane_b32 s0, v255, 7
	v_readlane_b32 s1, v255, 8
	s_andn2_b64 vcc, exec, s[0:1]
	s_waitcnt lgkmcnt(0)
	s_barrier
	s_cbranch_vccnz .LBB0_521
	v_readlane_b32 s0, v255, 25
	s_lshl_b32 s48, s0, 9
	s_lshl_b32 s8, s0, 4
	s_lshl_b32 s9, s0, 12
	s_lshl_b32 s6, s0, 8
	s_mov_b32 s7, s49
	s_lshl_b32 s10, s0, 10
	s_mov_b32 s11, s49
	s_lshl_b32 s20, s0, 1
	s_lshl_b32 s14, s0, 11
	s_mov_b32 s15, s49
	s_lshl_b32 s21, s0, 3
	s_lshl_b64 s[16:17], s[48:49], 2
	v_readlane_b32 s22, v255, 0
	v_readlane_b32 s1, v255, 26
	s_cmpk_eq_i32 s36, 0x100
	s_cselect_b32 s101, 0, -1
	s_branch .LBB0_274

.LBB0_273:
	s_cmp_eq_u32 s101, -1
	s_cbranch_scc1 .Llc_stride
	s_add_i32 s101, s101, 1
	v_readlane_b32 s100, v255, 0
	s_nop 3
	s_cmp_lt_u32 s101, 3
	s_cbranch_scc0 .Llc_k3
	s_mul_i32 s22, s101, 0x108
	s_add_i32 s22, s22, s100
	s_branch .LBB0_274
.Llc_k3:
	s_cmp_eq_u32 s101, 3
	s_cbranch_scc0 .Llc_k4
	s_cmp_lt_u32 s100, 24
	s_cbranch_scc0 .Llc_k3b
	s_lshr_b32 s22, s100, 3
	s_mul_i32 s22, s22, 0x108
	s_and_b32 s100, s100, 7
	s_add_i32 s22, s22, s100
	s_addk_i32 s22, 0x100
	s_branch .LBB0_274
.Llc_k3b:
	s_add_i32 s22, s100, 0x318
	s_branch .LBB0_274
.Llc_k4:
	s_cmp_gt_u32 s101, 4
	s_cbranch_scc1 .LBB0_521
	s_sub_i32 s100, s100, 24
	s_cmp_lt_u32 s100, 32
	s_cbranch_scc0 .LBB0_521
	s_cmp_lt_u32 s100, 24
	s_mov_b32 s22, 0x400
	s_cselect_b32 s22, 0x318, s22
	s_add_i32 s22, s22, s100
	s_branch .LBB0_274
